# P6 fused epilogue: conv(3)+SiLU row loop rewritten by hand (16 rows unrolled, window renamed instead of moved, packed f32 chain in natural element-pair layout, LDS rows prefetched, incremental store a
# speedup vs baseline: 1.0259x; 1.0105x over previous
.LBB0_2464:
	v_lshl_add_u32 v54, v52, 4, s38
	v_add_u32_e32 v54, v54, v53
	v_mul_lo_u32 v56, v53, s78
	v_lshlrev_b32_e32 v58, 1, v201
	v_mad_u32_u24 v56, v52, s82, v56
	v_add3_u32 v52, v56, v58, 16
	ds_read_b64 v[114:115], v52
	ds_read_b64 v[116:117], v52 offset:256
	v_lshl_add_u64 v[50:51], v[172:173], 1, s[4:5]
	v_mad_i64_i32 v[68:69], s[38:39], v54, s83, v[50:51]
	s_mov_b64 s[38:39], exec
	v_cmp_eq_u32_e32 vcc, 0, v53
	s_mov_b32 s58, s83
	s_mov_b32 s59, 0
	v_mov_b32_e32 v72, v35
	v_mov_b32_e32 v73, v45
	v_mov_b32_e32 v74, v37
	v_mov_b32_e32 v75, v43
	v_mov_b32_e32 v76, v34
	v_mov_b32_e32 v77, v44
	v_mov_b32_e32 v78, v36
	v_mov_b32_e32 v79, v42
	v_mov_b32_e32 v80, v39
	v_mov_b32_e32 v81, v47
	v_mov_b32_e32 v82, v41
	v_mov_b32_e32 v83, v49
	v_mov_b32_e32 v84, v38
	v_mov_b32_e32 v85, v46
	v_mov_b32_e32 v86, v40
	v_mov_b32_e32 v87, v48
	v_mov_b32_e32 v122, 0xbfb8aa3b
	v_mov_b32_e32 v123, 0xbfb8aa3b
	v_mov_b32_e32 v124, 1.0
	v_mov_b32_e32 v125, 1.0
	ds_read_b64 v[118:119], v52 offset:528
	ds_read_b64 v[120:121], v52 offset:784
	v_pk_fma_f32 v[96:97], v[10:11], v[72:73], v[2:3]
	v_pk_fma_f32 v[98:99], v[12:13], v[74:75], v[4:5]
	v_pk_fma_f32 v[100:101], v[14:15], v[76:77], v[6:7]
	v_pk_fma_f32 v[102:103], v[16:17], v[78:79], v[8:9]
	v_pk_fma_f32 v[96:97], v[18:19], v[80:81], v[96:97]
	v_pk_fma_f32 v[98:99], v[20:21], v[82:83], v[98:99]
	v_pk_fma_f32 v[100:101], v[22:23], v[84:85], v[100:101]
	v_pk_fma_f32 v[102:103], v[24:25], v[86:87], v[102:103]
	s_waitcnt lgkmcnt(2)
	v_lshlrev_b32_e32 v88, 16, v114
	v_and_b32_e32 v89, 0xffff0000, v114
	v_lshlrev_b32_e32 v90, 16, v115
	v_and_b32_e32 v91, 0xffff0000, v115
	v_lshlrev_b32_e32 v92, 16, v116
	v_and_b32_e32 v93, 0xffff0000, v116
	v_lshlrev_b32_e32 v94, 16, v117
	v_and_b32_e32 v95, 0xffff0000, v117
	v_pk_fma_f32 v[96:97], v[26:27], v[88:89], v[96:97]
	v_pk_fma_f32 v[98:99], v[28:29], v[90:91], v[98:99]
	v_pk_fma_f32 v[100:101], v[30:31], v[92:93], v[100:101]
	v_pk_fma_f32 v[102:103], v[32:33], v[94:95], v[102:103]
	v_pk_mul_f32 v[104:105], v[96:97], v[122:123]
	v_pk_mul_f32 v[106:107], v[98:99], v[122:123]
	v_exp_f32_e32 v104, v104
	v_exp_f32_e32 v105, v105
	v_exp_f32_e32 v106, v106
	v_exp_f32_e32 v107, v107
	v_pk_add_f32 v[104:105], v[104:105], v[124:125]
	v_pk_add_f32 v[106:107], v[106:107], v[124:125]
	v_rcp_f32_e32 v104, v104
	v_rcp_f32_e32 v105, v105
	v_rcp_f32_e32 v106, v106
	v_rcp_f32_e32 v107, v107
	v_pk_mul_f32 v[104:105], v[96:97], v[104:105]
	v_pk_mul_f32 v[106:107], v[98:99], v[106:107]
	v_pk_mul_f32 v[108:109], v[100:101], v[104:105]
	v_pk_mul_f32 v[110:111], v[102:103], v[106:107]
	v_cvt_pk_bf16_f32 v112, v108, v109
	v_cvt_pk_bf16_f32 v113, v110, v111
	global_store_dwordx2 v[68:69], v[112:113], off
	v_lshl_add_u64 v[68:69], v[68:69], 0, s[58:59]
	ds_read_b64 v[114:115], v52 offset:1056
	ds_read_b64 v[116:117], v52 offset:1312
	v_pk_fma_f32 v[96:97], v[10:11], v[80:81], v[2:3]
	v_pk_fma_f32 v[98:99], v[12:13], v[82:83], v[4:5]
	v_pk_fma_f32 v[100:101], v[14:15], v[84:85], v[6:7]
	v_pk_fma_f32 v[102:103], v[16:17], v[86:87], v[8:9]
	v_pk_fma_f32 v[96:97], v[18:19], v[88:89], v[96:97]
	v_pk_fma_f32 v[98:99], v[20:21], v[90:91], v[98:99]
	v_pk_fma_f32 v[100:101], v[22:23], v[92:93], v[100:101]
	v_pk_fma_f32 v[102:103], v[24:25], v[94:95], v[102:103]
	s_waitcnt lgkmcnt(2)
	v_lshlrev_b32_e32 v72, 16, v118
	v_and_b32_e32 v73, 0xffff0000, v118
	v_lshlrev_b32_e32 v74, 16, v119
	v_and_b32_e32 v75, 0xffff0000, v119
	v_lshlrev_b32_e32 v76, 16, v120
	v_and_b32_e32 v77, 0xffff0000, v120
	v_lshlrev_b32_e32 v78, 16, v121
	v_and_b32_e32 v79, 0xffff0000, v121
	v_pk_fma_f32 v[96:97], v[26:27], v[72:73], v[96:97]
	v_pk_fma_f32 v[98:99], v[28:29], v[74:75], v[98:99]
	v_pk_fma_f32 v[100:101], v[30:31], v[76:77], v[100:101]
	v_pk_fma_f32 v[102:103], v[32:33], v[78:79], v[102:103]
	v_pk_mul_f32 v[104:105], v[96:97], v[122:123]
	v_pk_mul_f32 v[106:107], v[98:99], v[122:123]
	v_exp_f32_e32 v104, v104
	v_exp_f32_e32 v105, v105
	v_exp_f32_e32 v106, v106
	v_exp_f32_e32 v107, v107
	v_pk_add_f32 v[104:105], v[104:105], v[124:125]
	v_pk_add_f32 v[106:107], v[106:107], v[124:125]
	v_rcp_f32_e32 v104, v104
	v_rcp_f32_e32 v105, v105
	v_rcp_f32_e32 v106, v106
	v_rcp_f32_e32 v107, v107
	v_pk_mul_f32 v[104:105], v[96:97], v[104:105]
	v_pk_mul_f32 v[106:107], v[98:99], v[106:107]
	v_pk_mul_f32 v[108:109], v[100:101], v[104:105]
	v_pk_mul_f32 v[110:111], v[102:103], v[106:107]
	v_cvt_pk_bf16_f32 v112, v108, v109
	v_cvt_pk_bf16_f32 v113, v110, v111
	global_store_dwordx2 v[68:69], v[112:113], off
	v_lshl_add_u64 v[68:69], v[68:69], 0, s[58:59]
	ds_read_b64 v[118:119], v52 offset:1584
	ds_read_b64 v[120:121], v52 offset:1840
	v_pk_fma_f32 v[96:97], v[10:11], v[88:89], v[2:3]
	v_pk_fma_f32 v[98:99], v[12:13], v[90:91], v[4:5]
	v_pk_fma_f32 v[100:101], v[14:15], v[92:93], v[6:7]
	v_pk_fma_f32 v[102:103], v[16:17], v[94:95], v[8:9]
	v_pk_fma_f32 v[96:97], v[18:19], v[72:73], v[96:97]
	v_pk_fma_f32 v[98:99], v[20:21], v[74:75], v[98:99]
	v_pk_fma_f32 v[100:101], v[22:23], v[76:77], v[100:101]
	v_pk_fma_f32 v[102:103], v[24:25], v[78:79], v[102:103]
	s_waitcnt lgkmcnt(2)
	v_lshlrev_b32_e32 v80, 16, v114
	v_and_b32_e32 v81, 0xffff0000, v114
	v_lshlrev_b32_e32 v82, 16, v115
	v_and_b32_e32 v83, 0xffff0000, v115
	v_lshlrev_b32_e32 v84, 16, v116
	v_and_b32_e32 v85, 0xffff0000, v116
	v_lshlrev_b32_e32 v86, 16, v117
	v_and_b32_e32 v87, 0xffff0000, v117
	v_pk_fma_f32 v[96:97], v[26:27], v[80:81], v[96:97]
	v_pk_fma_f32 v[98:99], v[28:29], v[82:83], v[98:99]
	v_pk_fma_f32 v[100:101], v[30:31], v[84:85], v[100:101]
	v_pk_fma_f32 v[102:103], v[32:33], v[86:87], v[102:103]
	v_pk_mul_f32 v[104:105], v[96:97], v[122:123]
	v_pk_mul_f32 v[106:107], v[98:99], v[122:123]
	v_exp_f32_e32 v104, v104
	v_exp_f32_e32 v105, v105
	v_exp_f32_e32 v106, v106
	v_exp_f32_e32 v107, v107
	v_pk_add_f32 v[104:105], v[104:105], v[124:125]
	v_pk_add_f32 v[106:107], v[106:107], v[124:125]
	v_rcp_f32_e32 v104, v104
	v_rcp_f32_e32 v105, v105
	v_rcp_f32_e32 v106, v106
	v_rcp_f32_e32 v107, v107
	v_pk_mul_f32 v[104:105], v[96:97], v[104:105]
	v_pk_mul_f32 v[106:107], v[98:99], v[106:107]
	v_pk_mul_f32 v[108:109], v[100:101], v[104:105]
	v_pk_mul_f32 v[110:111], v[102:103], v[106:107]
	v_cvt_pk_bf16_f32 v112, v108, v109
	v_cvt_pk_bf16_f32 v113, v110, v111
	global_store_dwordx2 v[68:69], v[112:113], off
	v_lshl_add_u64 v[68:69], v[68:69], 0, s[58:59]
	ds_read_b64 v[114:115], v52 offset:2112
	ds_read_b64 v[116:117], v52 offset:2368
	v_pk_fma_f32 v[96:97], v[10:11], v[72:73], v[2:3]
	v_pk_fma_f32 v[98:99], v[12:13], v[74:75], v[4:5]
	v_pk_fma_f32 v[100:101], v[14:15], v[76:77], v[6:7]
	v_pk_fma_f32 v[102:103], v[16:17], v[78:79], v[8:9]
	v_pk_fma_f32 v[96:97], v[18:19], v[80:81], v[96:97]
	v_pk_fma_f32 v[98:99], v[20:21], v[82:83], v[98:99]
	v_pk_fma_f32 v[100:101], v[22:23], v[84:85], v[100:101]
	v_pk_fma_f32 v[102:103], v[24:25], v[86:87], v[102:103]
	s_waitcnt lgkmcnt(2)
	v_lshlrev_b32_e32 v88, 16, v118
	v_and_b32_e32 v89, 0xffff0000, v118
	v_lshlrev_b32_e32 v90, 16, v119
	v_and_b32_e32 v91, 0xffff0000, v119
	v_lshlrev_b32_e32 v92, 16, v120
	v_and_b32_e32 v93, 0xffff0000, v120
	v_lshlrev_b32_e32 v94, 16, v121
	v_and_b32_e32 v95, 0xffff0000, v121
	v_pk_fma_f32 v[96:97], v[26:27], v[88:89], v[96:97]
	v_pk_fma_f32 v[98:99], v[28:29], v[90:91], v[98:99]
	v_pk_fma_f32 v[100:101], v[30:31], v[92:93], v[100:101]
	v_pk_fma_f32 v[102:103], v[32:33], v[94:95], v[102:103]
	v_pk_mul_f32 v[104:105], v[96:97], v[122:123]
	v_pk_mul_f32 v[106:107], v[98:99], v[122:123]
	v_exp_f32_e32 v104, v104
	v_exp_f32_e32 v105, v105
	v_exp_f32_e32 v106, v106
	v_exp_f32_e32 v107, v107
	v_pk_add_f32 v[104:105], v[104:105], v[124:125]
	v_pk_add_f32 v[106:107], v[106:107], v[124:125]
	v_rcp_f32_e32 v104, v104
	v_rcp_f32_e32 v105, v105
	v_rcp_f32_e32 v106, v106
	v_rcp_f32_e32 v107, v107
	v_pk_mul_f32 v[104:105], v[96:97], v[104:105]
	v_pk_mul_f32 v[106:107], v[98:99], v[106:107]
	v_pk_mul_f32 v[108:109], v[100:101], v[104:105]
	v_pk_mul_f32 v[110:111], v[102:103], v[106:107]
	v_cvt_pk_bf16_f32 v112, v108, v109
	v_cvt_pk_bf16_f32 v113, v110, v111
	global_store_dwordx2 v[68:69], v[112:113], off
	v_lshl_add_u64 v[68:69], v[68:69], 0, s[58:59]
	ds_read_b64 v[118:119], v52 offset:2640
	ds_read_b64 v[120:121], v52 offset:2896
	v_pk_fma_f32 v[96:97], v[10:11], v[80:81], v[2:3]
	v_pk_fma_f32 v[98:99], v[12:13], v[82:83], v[4:5]
	v_pk_fma_f32 v[100:101], v[14:15], v[84:85], v[6:7]
	v_pk_fma_f32 v[102:103], v[16:17], v[86:87], v[8:9]
	v_pk_fma_f32 v[96:97], v[18:19], v[88:89], v[96:97]
	v_pk_fma_f32 v[98:99], v[20:21], v[90:91], v[98:99]
	v_pk_fma_f32 v[100:101], v[22:23], v[92:93], v[100:101]
	v_pk_fma_f32 v[102:103], v[24:25], v[94:95], v[102:103]
	s_waitcnt lgkmcnt(2)
	v_lshlrev_b32_e32 v72, 16, v114
	v_and_b32_e32 v73, 0xffff0000, v114
	v_lshlrev_b32_e32 v74, 16, v115
	v_and_b32_e32 v75, 0xffff0000, v115
	v_lshlrev_b32_e32 v76, 16, v116
	v_and_b32_e32 v77, 0xffff0000, v116
	v_lshlrev_b32_e32 v78, 16, v117
	v_and_b32_e32 v79, 0xffff0000, v117
	v_pk_fma_f32 v[96:97], v[26:27], v[72:73], v[96:97]
	v_pk_fma_f32 v[98:99], v[28:29], v[74:75], v[98:99]
	v_pk_fma_f32 v[100:101], v[30:31], v[76:77], v[100:101]
	v_pk_fma_f32 v[102:103], v[32:33], v[78:79], v[102:103]
	v_pk_mul_f32 v[104:105], v[96:97], v[122:123]
	v_pk_mul_f32 v[106:107], v[98:99], v[122:123]
	v_exp_f32_e32 v104, v104
	v_exp_f32_e32 v105, v105
	v_exp_f32_e32 v106, v106
	v_exp_f32_e32 v107, v107
	v_pk_add_f32 v[104:105], v[104:105], v[124:125]
	v_pk_add_f32 v[106:107], v[106:107], v[124:125]
	v_rcp_f32_e32 v104, v104
	v_rcp_f32_e32 v105, v105
	v_rcp_f32_e32 v106, v106
	v_rcp_f32_e32 v107, v107
	v_pk_mul_f32 v[104:105], v[96:97], v[104:105]
	v_pk_mul_f32 v[106:107], v[98:99], v[106:107]
	v_pk_mul_f32 v[108:109], v[100:101], v[104:105]
	v_pk_mul_f32 v[110:111], v[102:103], v[106:107]
	v_cvt_pk_bf16_f32 v112, v108, v109
	v_cvt_pk_bf16_f32 v113, v110, v111
	global_store_dwordx2 v[68:69], v[112:113], off
	v_lshl_add_u64 v[68:69], v[68:69], 0, s[58:59]
	ds_read_b64 v[114:115], v52 offset:3168
	ds_read_b64 v[116:117], v52 offset:3424
	v_pk_fma_f32 v[96:97], v[10:11], v[88:89], v[2:3]
	v_pk_fma_f32 v[98:99], v[12:13], v[90:91], v[4:5]
	v_pk_fma_f32 v[100:101], v[14:15], v[92:93], v[6:7]
	v_pk_fma_f32 v[102:103], v[16:17], v[94:95], v[8:9]
	v_pk_fma_f32 v[96:97], v[18:19], v[72:73], v[96:97]
	v_pk_fma_f32 v[98:99], v[20:21], v[74:75], v[98:99]
	v_pk_fma_f32 v[100:101], v[22:23], v[76:77], v[100:101]
	v_pk_fma_f32 v[102:103], v[24:25], v[78:79], v[102:103]
	s_waitcnt lgkmcnt(2)
	v_lshlrev_b32_e32 v80, 16, v118
	v_and_b32_e32 v81, 0xffff0000, v118
	v_lshlrev_b32_e32 v82, 16, v119
	v_and_b32_e32 v83, 0xffff0000, v119
	v_lshlrev_b32_e32 v84, 16, v120
	v_and_b32_e32 v85, 0xffff0000, v120
	v_lshlrev_b32_e32 v86, 16, v121
	v_and_b32_e32 v87, 0xffff0000, v121
	v_pk_fma_f32 v[96:97], v[26:27], v[80:81], v[96:97]
	v_pk_fma_f32 v[98:99], v[28:29], v[82:83], v[98:99]
	v_pk_fma_f32 v[100:101], v[30:31], v[84:85], v[100:101]
	v_pk_fma_f32 v[102:103], v[32:33], v[86:87], v[102:103]
	v_pk_mul_f32 v[104:105], v[96:97], v[122:123]
	v_pk_mul_f32 v[106:107], v[98:99], v[122:123]
	v_exp_f32_e32 v104, v104
	v_exp_f32_e32 v105, v105
	v_exp_f32_e32 v106, v106
	v_exp_f32_e32 v107, v107
	v_pk_add_f32 v[104:105], v[104:105], v[124:125]
	v_pk_add_f32 v[106:107], v[106:107], v[124:125]
	v_rcp_f32_e32 v104, v104
	v_rcp_f32_e32 v105, v105
	v_rcp_f32_e32 v106, v106
	v_rcp_f32_e32 v107, v107
	v_pk_mul_f32 v[104:105], v[96:97], v[104:105]
	v_pk_mul_f32 v[106:107], v[98:99], v[106:107]
	v_pk_mul_f32 v[108:109], v[100:101], v[104:105]
	v_pk_mul_f32 v[110:111], v[102:103], v[106:107]
	v_cvt_pk_bf16_f32 v112, v108, v109
	v_cvt_pk_bf16_f32 v113, v110, v111
	global_store_dwordx2 v[68:69], v[112:113], off
	v_lshl_add_u64 v[68:69], v[68:69], 0, s[58:59]
	ds_read_b64 v[118:119], v52 offset:3696
	ds_read_b64 v[120:121], v52 offset:3952
	v_pk_fma_f32 v[96:97], v[10:11], v[72:73], v[2:3]
	v_pk_fma_f32 v[98:99], v[12:13], v[74:75], v[4:5]
	v_pk_fma_f32 v[100:101], v[14:15], v[76:77], v[6:7]
	v_pk_fma_f32 v[102:103], v[16:17], v[78:79], v[8:9]
	v_pk_fma_f32 v[96:97], v[18:19], v[80:81], v[96:97]
	v_pk_fma_f32 v[98:99], v[20:21], v[82:83], v[98:99]
	v_pk_fma_f32 v[100:101], v[22:23], v[84:85], v[100:101]
	v_pk_fma_f32 v[102:103], v[24:25], v[86:87], v[102:103]
	s_waitcnt lgkmcnt(2)
	v_lshlrev_b32_e32 v88, 16, v114
	v_and_b32_e32 v89, 0xffff0000, v114
	v_lshlrev_b32_e32 v90, 16, v115
	v_and_b32_e32 v91, 0xffff0000, v115
	v_lshlrev_b32_e32 v92, 16, v116
	v_and_b32_e32 v93, 0xffff0000, v116
	v_lshlrev_b32_e32 v94, 16, v117
	v_and_b32_e32 v95, 0xffff0000, v117
	v_pk_fma_f32 v[96:97], v[26:27], v[88:89], v[96:97]
	v_pk_fma_f32 v[98:99], v[28:29], v[90:91], v[98:99]
	v_pk_fma_f32 v[100:101], v[30:31], v[92:93], v[100:101]
	v_pk_fma_f32 v[102:103], v[32:33], v[94:95], v[102:103]
	v_pk_mul_f32 v[104:105], v[96:97], v[122:123]
	v_pk_mul_f32 v[106:107], v[98:99], v[122:123]
	v_exp_f32_e32 v104, v104
	v_exp_f32_e32 v105, v105
	v_exp_f32_e32 v106, v106
	v_exp_f32_e32 v107, v107
	v_pk_add_f32 v[104:105], v[104:105], v[124:125]
	v_pk_add_f32 v[106:107], v[106:107], v[124:125]
	v_rcp_f32_e32 v104, v104
	v_rcp_f32_e32 v105, v105
	v_rcp_f32_e32 v106, v106
	v_rcp_f32_e32 v107, v107
	v_pk_mul_f32 v[104:105], v[96:97], v[104:105]
	v_pk_mul_f32 v[106:107], v[98:99], v[106:107]
	v_pk_mul_f32 v[108:109], v[100:101], v[104:105]
	v_pk_mul_f32 v[110:111], v[102:103], v[106:107]
	v_cvt_pk_bf16_f32 v112, v108, v109
	v_cvt_pk_bf16_f32 v113, v110, v111
	global_store_dwordx2 v[68:69], v[112:113], off
	v_lshl_add_u64 v[68:69], v[68:69], 0, s[58:59]
	ds_read_b64 v[114:115], v52 offset:4224
	ds_read_b64 v[116:117], v52 offset:4480
	v_pk_fma_f32 v[96:97], v[10:11], v[80:81], v[2:3]
	v_pk_fma_f32 v[98:99], v[12:13], v[82:83], v[4:5]
	v_pk_fma_f32 v[100:101], v[14:15], v[84:85], v[6:7]
	v_pk_fma_f32 v[102:103], v[16:17], v[86:87], v[8:9]
	v_pk_fma_f32 v[96:97], v[18:19], v[88:89], v[96:97]
	v_pk_fma_f32 v[98:99], v[20:21], v[90:91], v[98:99]
	v_pk_fma_f32 v[100:101], v[22:23], v[92:93], v[100:101]
	v_pk_fma_f32 v[102:103], v[24:25], v[94:95], v[102:103]
	s_waitcnt lgkmcnt(2)
	v_lshlrev_b32_e32 v72, 16, v118
	v_and_b32_e32 v73, 0xffff0000, v118
	v_lshlrev_b32_e32 v74, 16, v119
	v_and_b32_e32 v75, 0xffff0000, v119
	v_lshlrev_b32_e32 v76, 16, v120
	v_and_b32_e32 v77, 0xffff0000, v120
	v_lshlrev_b32_e32 v78, 16, v121
	v_and_b32_e32 v79, 0xffff0000, v121
	v_pk_fma_f32 v[96:97], v[26:27], v[72:73], v[96:97]
	v_pk_fma_f32 v[98:99], v[28:29], v[74:75], v[98:99]
	v_pk_fma_f32 v[100:101], v[30:31], v[76:77], v[100:101]
	v_pk_fma_f32 v[102:103], v[32:33], v[78:79], v[102:103]
	v_pk_mul_f32 v[104:105], v[96:97], v[122:123]
	v_pk_mul_f32 v[106:107], v[98:99], v[122:123]
	v_exp_f32_e32 v104, v104
	v_exp_f32_e32 v105, v105
	v_exp_f32_e32 v106, v106
	v_exp_f32_e32 v107, v107
	v_pk_add_f32 v[104:105], v[104:105], v[124:125]
	v_pk_add_f32 v[106:107], v[106:107], v[124:125]
	v_rcp_f32_e32 v104, v104
	v_rcp_f32_e32 v105, v105
	v_rcp_f32_e32 v106, v106
	v_rcp_f32_e32 v107, v107
	v_pk_mul_f32 v[104:105], v[96:97], v[104:105]
	v_pk_mul_f32 v[106:107], v[98:99], v[106:107]
	v_pk_mul_f32 v[108:109], v[100:101], v[104:105]
	v_pk_mul_f32 v[110:111], v[102:103], v[106:107]
	v_cvt_pk_bf16_f32 v112, v108, v109
	v_cvt_pk_bf16_f32 v113, v110, v111
	global_store_dwordx2 v[68:69], v[112:113], off
	v_lshl_add_u64 v[68:69], v[68:69], 0, s[58:59]
	ds_read_b64 v[118:119], v52 offset:4752
	ds_read_b64 v[120:121], v52 offset:5008
	v_pk_fma_f32 v[96:97], v[10:11], v[88:89], v[2:3]
	v_pk_fma_f32 v[98:99], v[12:13], v[90:91], v[4:5]
	v_pk_fma_f32 v[100:101], v[14:15], v[92:93], v[6:7]
	v_pk_fma_f32 v[102:103], v[16:17], v[94:95], v[8:9]
	v_pk_fma_f32 v[96:97], v[18:19], v[72:73], v[96:97]
	v_pk_fma_f32 v[98:99], v[20:21], v[74:75], v[98:99]
	v_pk_fma_f32 v[100:101], v[22:23], v[76:77], v[100:101]
	v_pk_fma_f32 v[102:103], v[24:25], v[78:79], v[102:103]
	s_waitcnt lgkmcnt(2)
	v_lshlrev_b32_e32 v80, 16, v114
	v_and_b32_e32 v81, 0xffff0000, v114
	v_lshlrev_b32_e32 v82, 16, v115
	v_and_b32_e32 v83, 0xffff0000, v115
	v_lshlrev_b32_e32 v84, 16, v116
	v_and_b32_e32 v85, 0xffff0000, v116
	v_lshlrev_b32_e32 v86, 16, v117
	v_and_b32_e32 v87, 0xffff0000, v117
	v_pk_fma_f32 v[96:97], v[26:27], v[80:81], v[96:97]
	v_pk_fma_f32 v[98:99], v[28:29], v[82:83], v[98:99]
	v_pk_fma_f32 v[100:101], v[30:31], v[84:85], v[100:101]
	v_pk_fma_f32 v[102:103], v[32:33], v[86:87], v[102:103]
	v_pk_mul_f32 v[104:105], v[96:97], v[122:123]
	v_pk_mul_f32 v[106:107], v[98:99], v[122:123]
	v_exp_f32_e32 v104, v104
	v_exp_f32_e32 v105, v105
	v_exp_f32_e32 v106, v106
	v_exp_f32_e32 v107, v107
	v_pk_add_f32 v[104:105], v[104:105], v[124:125]
	v_pk_add_f32 v[106:107], v[106:107], v[124:125]
	v_rcp_f32_e32 v104, v104
	v_rcp_f32_e32 v105, v105
	v_rcp_f32_e32 v106, v106
	v_rcp_f32_e32 v107, v107
	v_pk_mul_f32 v[104:105], v[96:97], v[104:105]
	v_pk_mul_f32 v[106:107], v[98:99], v[106:107]
	v_pk_mul_f32 v[108:109], v[100:101], v[104:105]
	v_pk_mul_f32 v[110:111], v[102:103], v[106:107]
	v_cvt_pk_bf16_f32 v112, v108, v109
	v_cvt_pk_bf16_f32 v113, v110, v111
	global_store_dwordx2 v[68:69], v[112:113], off
	v_lshl_add_u64 v[68:69], v[68:69], 0, s[58:59]
	ds_read_b64 v[114:115], v52 offset:5280
	ds_read_b64 v[116:117], v52 offset:5536
	v_pk_fma_f32 v[96:97], v[10:11], v[72:73], v[2:3]
	v_pk_fma_f32 v[98:99], v[12:13], v[74:75], v[4:5]
	v_pk_fma_f32 v[100:101], v[14:15], v[76:77], v[6:7]
	v_pk_fma_f32 v[102:103], v[16:17], v[78:79], v[8:9]
	v_pk_fma_f32 v[96:97], v[18:19], v[80:81], v[96:97]
	v_pk_fma_f32 v[98:99], v[20:21], v[82:83], v[98:99]
	v_pk_fma_f32 v[100:101], v[22:23], v[84:85], v[100:101]
	v_pk_fma_f32 v[102:103], v[24:25], v[86:87], v[102:103]
	s_waitcnt lgkmcnt(2)
	v_lshlrev_b32_e32 v88, 16, v118
	v_and_b32_e32 v89, 0xffff0000, v118
	v_lshlrev_b32_e32 v90, 16, v119
	v_and_b32_e32 v91, 0xffff0000, v119
	v_lshlrev_b32_e32 v92, 16, v120
	v_and_b32_e32 v93, 0xffff0000, v120
	v_lshlrev_b32_e32 v94, 16, v121
	v_and_b32_e32 v95, 0xffff0000, v121
	v_pk_fma_f32 v[96:97], v[26:27], v[88:89], v[96:97]
	v_pk_fma_f32 v[98:99], v[28:29], v[90:91], v[98:99]
	v_pk_fma_f32 v[100:101], v[30:31], v[92:93], v[100:101]
	v_pk_fma_f32 v[102:103], v[32:33], v[94:95], v[102:103]
	v_pk_mul_f32 v[104:105], v[96:97], v[122:123]
	v_pk_mul_f32 v[106:107], v[98:99], v[122:123]
	v_exp_f32_e32 v104, v104
	v_exp_f32_e32 v105, v105
	v_exp_f32_e32 v106, v106
	v_exp_f32_e32 v107, v107
	v_pk_add_f32 v[104:105], v[104:105], v[124:125]
	v_pk_add_f32 v[106:107], v[106:107], v[124:125]
	v_rcp_f32_e32 v104, v104
	v_rcp_f32_e32 v105, v105
	v_rcp_f32_e32 v106, v106
	v_rcp_f32_e32 v107, v107
	v_pk_mul_f32 v[104:105], v[96:97], v[104:105]
	v_pk_mul_f32 v[106:107], v[98:99], v[106:107]
	v_pk_mul_f32 v[108:109], v[100:101], v[104:105]
	v_pk_mul_f32 v[110:111], v[102:103], v[106:107]
	v_cvt_pk_bf16_f32 v112, v108, v109
	v_cvt_pk_bf16_f32 v113, v110, v111
	global_store_dwordx2 v[68:69], v[112:113], off
	v_lshl_add_u64 v[68:69], v[68:69], 0, s[58:59]
	ds_read_b64 v[118:119], v52 offset:5808
	ds_read_b64 v[120:121], v52 offset:6064
	v_pk_fma_f32 v[96:97], v[10:11], v[80:81], v[2:3]
	v_pk_fma_f32 v[98:99], v[12:13], v[82:83], v[4:5]
	v_pk_fma_f32 v[100:101], v[14:15], v[84:85], v[6:7]
	v_pk_fma_f32 v[102:103], v[16:17], v[86:87], v[8:9]
	v_pk_fma_f32 v[96:97], v[18:19], v[88:89], v[96:97]
	v_pk_fma_f32 v[98:99], v[20:21], v[90:91], v[98:99]
	v_pk_fma_f32 v[100:101], v[22:23], v[92:93], v[100:101]
	v_pk_fma_f32 v[102:103], v[24:25], v[94:95], v[102:103]
	s_waitcnt lgkmcnt(2)
	v_lshlrev_b32_e32 v72, 16, v114
	v_and_b32_e32 v73, 0xffff0000, v114
	v_lshlrev_b32_e32 v74, 16, v115
	v_and_b32_e32 v75, 0xffff0000, v115
	v_lshlrev_b32_e32 v76, 16, v116
	v_and_b32_e32 v77, 0xffff0000, v116
	v_lshlrev_b32_e32 v78, 16, v117
	v_and_b32_e32 v79, 0xffff0000, v117
	v_pk_fma_f32 v[96:97], v[26:27], v[72:73], v[96:97]
	v_pk_fma_f32 v[98:99], v[28:29], v[74:75], v[98:99]
	v_pk_fma_f32 v[100:101], v[30:31], v[76:77], v[100:101]
	v_pk_fma_f32 v[102:103], v[32:33], v[78:79], v[102:103]
	v_pk_mul_f32 v[104:105], v[96:97], v[122:123]
	v_pk_mul_f32 v[106:107], v[98:99], v[122:123]
	v_exp_f32_e32 v104, v104
	v_exp_f32_e32 v105, v105
	v_exp_f32_e32 v106, v106
	v_exp_f32_e32 v107, v107
	v_pk_add_f32 v[104:105], v[104:105], v[124:125]
	v_pk_add_f32 v[106:107], v[106:107], v[124:125]
	v_rcp_f32_e32 v104, v104
	v_rcp_f32_e32 v105, v105
	v_rcp_f32_e32 v106, v106
	v_rcp_f32_e32 v107, v107
	v_pk_mul_f32 v[104:105], v[96:97], v[104:105]
	v_pk_mul_f32 v[106:107], v[98:99], v[106:107]
	v_pk_mul_f32 v[108:109], v[100:101], v[104:105]
	v_pk_mul_f32 v[110:111], v[102:103], v[106:107]
	v_cvt_pk_bf16_f32 v112, v108, v109
	v_cvt_pk_bf16_f32 v113, v110, v111
	global_store_dwordx2 v[68:69], v[112:113], off
	v_lshl_add_u64 v[68:69], v[68:69], 0, s[58:59]
	ds_read_b64 v[114:115], v52 offset:6336
	ds_read_b64 v[116:117], v52 offset:6592
	v_pk_fma_f32 v[96:97], v[10:11], v[88:89], v[2:3]
	v_pk_fma_f32 v[98:99], v[12:13], v[90:91], v[4:5]
	v_pk_fma_f32 v[100:101], v[14:15], v[92:93], v[6:7]
	v_pk_fma_f32 v[102:103], v[16:17], v[94:95], v[8:9]
	v_pk_fma_f32 v[96:97], v[18:19], v[72:73], v[96:97]
	v_pk_fma_f32 v[98:99], v[20:21], v[74:75], v[98:99]
	v_pk_fma_f32 v[100:101], v[22:23], v[76:77], v[100:101]
	v_pk_fma_f32 v[102:103], v[24:25], v[78:79], v[102:103]
	s_waitcnt lgkmcnt(2)
	v_lshlrev_b32_e32 v80, 16, v118
	v_and_b32_e32 v81, 0xffff0000, v118
	v_lshlrev_b32_e32 v82, 16, v119
	v_and_b32_e32 v83, 0xffff0000, v119
	v_lshlrev_b32_e32 v84, 16, v120
	v_and_b32_e32 v85, 0xffff0000, v120
	v_lshlrev_b32_e32 v86, 16, v121
	v_and_b32_e32 v87, 0xffff0000, v121
	v_pk_fma_f32 v[96:97], v[26:27], v[80:81], v[96:97]
	v_pk_fma_f32 v[98:99], v[28:29], v[82:83], v[98:99]
	v_pk_fma_f32 v[100:101], v[30:31], v[84:85], v[100:101]
	v_pk_fma_f32 v[102:103], v[32:33], v[86:87], v[102:103]
	v_pk_mul_f32 v[104:105], v[96:97], v[122:123]
	v_pk_mul_f32 v[106:107], v[98:99], v[122:123]
	v_exp_f32_e32 v104, v104
	v_exp_f32_e32 v105, v105
	v_exp_f32_e32 v106, v106
	v_exp_f32_e32 v107, v107
	v_pk_add_f32 v[104:105], v[104:105], v[124:125]
	v_pk_add_f32 v[106:107], v[106:107], v[124:125]
	v_rcp_f32_e32 v104, v104
	v_rcp_f32_e32 v105, v105
	v_rcp_f32_e32 v106, v106
	v_rcp_f32_e32 v107, v107
	v_pk_mul_f32 v[104:105], v[96:97], v[104:105]
	v_pk_mul_f32 v[106:107], v[98:99], v[106:107]
	v_pk_mul_f32 v[108:109], v[100:101], v[104:105]
	v_pk_mul_f32 v[110:111], v[102:103], v[106:107]
	v_cvt_pk_bf16_f32 v112, v108, v109
	v_cvt_pk_bf16_f32 v113, v110, v111
	global_store_dwordx2 v[68:69], v[112:113], off
	v_lshl_add_u64 v[68:69], v[68:69], 0, s[58:59]
	ds_read_b64 v[118:119], v52 offset:6864
	ds_read_b64 v[120:121], v52 offset:7120
	v_pk_fma_f32 v[96:97], v[10:11], v[72:73], v[2:3]
	v_pk_fma_f32 v[98:99], v[12:13], v[74:75], v[4:5]
	v_pk_fma_f32 v[100:101], v[14:15], v[76:77], v[6:7]
	v_pk_fma_f32 v[102:103], v[16:17], v[78:79], v[8:9]
	v_pk_fma_f32 v[96:97], v[18:19], v[80:81], v[96:97]
	v_pk_fma_f32 v[98:99], v[20:21], v[82:83], v[98:99]
	v_pk_fma_f32 v[100:101], v[22:23], v[84:85], v[100:101]
	v_pk_fma_f32 v[102:103], v[24:25], v[86:87], v[102:103]
	s_waitcnt lgkmcnt(2)
	v_lshlrev_b32_e32 v88, 16, v114
	v_and_b32_e32 v89, 0xffff0000, v114
	v_lshlrev_b32_e32 v90, 16, v115
	v_and_b32_e32 v91, 0xffff0000, v115
	v_lshlrev_b32_e32 v92, 16, v116
	v_and_b32_e32 v93, 0xffff0000, v116
	v_lshlrev_b32_e32 v94, 16, v117
	v_and_b32_e32 v95, 0xffff0000, v117
	v_pk_fma_f32 v[96:97], v[26:27], v[88:89], v[96:97]
	v_pk_fma_f32 v[98:99], v[28:29], v[90:91], v[98:99]
	v_pk_fma_f32 v[100:101], v[30:31], v[92:93], v[100:101]
	v_pk_fma_f32 v[102:103], v[32:33], v[94:95], v[102:103]
	v_pk_mul_f32 v[104:105], v[96:97], v[122:123]
	v_pk_mul_f32 v[106:107], v[98:99], v[122:123]
	v_exp_f32_e32 v104, v104
	v_exp_f32_e32 v105, v105
	v_exp_f32_e32 v106, v106
	v_exp_f32_e32 v107, v107
	v_pk_add_f32 v[104:105], v[104:105], v[124:125]
	v_pk_add_f32 v[106:107], v[106:107], v[124:125]
	v_rcp_f32_e32 v104, v104
	v_rcp_f32_e32 v105, v105
	v_rcp_f32_e32 v106, v106
	v_rcp_f32_e32 v107, v107
	v_pk_mul_f32 v[104:105], v[96:97], v[104:105]
	v_pk_mul_f32 v[106:107], v[98:99], v[106:107]
	v_pk_mul_f32 v[108:109], v[100:101], v[104:105]
	v_pk_mul_f32 v[110:111], v[102:103], v[106:107]
	v_cvt_pk_bf16_f32 v112, v108, v109
	v_cvt_pk_bf16_f32 v113, v110, v111
	global_store_dwordx2 v[68:69], v[112:113], off
	v_lshl_add_u64 v[68:69], v[68:69], 0, s[58:59]
	ds_read_b64 v[114:115], v52 offset:7392
	ds_read_b64 v[116:117], v52 offset:7648
	v_pk_fma_f32 v[96:97], v[10:11], v[80:81], v[2:3]
	v_pk_fma_f32 v[98:99], v[12:13], v[82:83], v[4:5]
	v_pk_fma_f32 v[100:101], v[14:15], v[84:85], v[6:7]
	v_pk_fma_f32 v[102:103], v[16:17], v[86:87], v[8:9]
	v_pk_fma_f32 v[96:97], v[18:19], v[88:89], v[96:97]
	v_pk_fma_f32 v[98:99], v[20:21], v[90:91], v[98:99]
	v_pk_fma_f32 v[100:101], v[22:23], v[92:93], v[100:101]
	v_pk_fma_f32 v[102:103], v[24:25], v[94:95], v[102:103]
	s_waitcnt lgkmcnt(2)
	v_lshlrev_b32_e32 v72, 16, v118
	v_and_b32_e32 v73, 0xffff0000, v118
	v_lshlrev_b32_e32 v74, 16, v119
	v_and_b32_e32 v75, 0xffff0000, v119
	v_lshlrev_b32_e32 v76, 16, v120
	v_and_b32_e32 v77, 0xffff0000, v120
	v_lshlrev_b32_e32 v78, 16, v121
	v_and_b32_e32 v79, 0xffff0000, v121
	v_pk_fma_f32 v[96:97], v[26:27], v[72:73], v[96:97]
	v_pk_fma_f32 v[98:99], v[28:29], v[74:75], v[98:99]
	v_pk_fma_f32 v[100:101], v[30:31], v[76:77], v[100:101]
	v_pk_fma_f32 v[102:103], v[32:33], v[78:79], v[102:103]
	v_pk_mul_f32 v[104:105], v[96:97], v[122:123]
	v_pk_mul_f32 v[106:107], v[98:99], v[122:123]
	v_exp_f32_e32 v104, v104
	v_exp_f32_e32 v105, v105
	v_exp_f32_e32 v106, v106
	v_exp_f32_e32 v107, v107
	v_pk_add_f32 v[104:105], v[104:105], v[124:125]
	v_pk_add_f32 v[106:107], v[106:107], v[124:125]
	v_rcp_f32_e32 v104, v104
	v_rcp_f32_e32 v105, v105
	v_rcp_f32_e32 v106, v106
	v_rcp_f32_e32 v107, v107
	v_pk_mul_f32 v[104:105], v[96:97], v[104:105]
	v_pk_mul_f32 v[106:107], v[98:99], v[106:107]
	v_pk_mul_f32 v[108:109], v[100:101], v[104:105]
	v_pk_mul_f32 v[110:111], v[102:103], v[106:107]
	v_cvt_pk_bf16_f32 v112, v108, v109
	v_cvt_pk_bf16_f32 v113, v110, v111
	global_store_dwordx2 v[68:69], v[112:113], off
	v_lshl_add_u64 v[68:69], v[68:69], 0, s[58:59]
	s_and_b64 exec, exec, vcc
	ds_read_b64 v[118:119], v52 offset:7920
	ds_read_b64 v[120:121], v52 offset:8176
	v_pk_fma_f32 v[96:97], v[10:11], v[88:89], v[2:3]
	v_pk_fma_f32 v[98:99], v[12:13], v[90:91], v[4:5]
	v_pk_fma_f32 v[100:101], v[14:15], v[92:93], v[6:7]
	v_pk_fma_f32 v[102:103], v[16:17], v[94:95], v[8:9]
	v_pk_fma_f32 v[96:97], v[18:19], v[72:73], v[96:97]
	v_pk_fma_f32 v[98:99], v[20:21], v[74:75], v[98:99]
	v_pk_fma_f32 v[100:101], v[22:23], v[76:77], v[100:101]
	v_pk_fma_f32 v[102:103], v[24:25], v[78:79], v[102:103]
	s_waitcnt lgkmcnt(2)
	v_lshlrev_b32_e32 v80, 16, v114
	v_and_b32_e32 v81, 0xffff0000, v114
	v_lshlrev_b32_e32 v82, 16, v115
	v_and_b32_e32 v83, 0xffff0000, v115
	v_lshlrev_b32_e32 v84, 16, v116
	v_and_b32_e32 v85, 0xffff0000, v116
	v_lshlrev_b32_e32 v86, 16, v117
	v_and_b32_e32 v87, 0xffff0000, v117
	v_pk_fma_f32 v[96:97], v[26:27], v[80:81], v[96:97]
	v_pk_fma_f32 v[98:99], v[28:29], v[82:83], v[98:99]
	v_pk_fma_f32 v[100:101], v[30:31], v[84:85], v[100:101]
	v_pk_fma_f32 v[102:103], v[32:33], v[86:87], v[102:103]
	v_pk_mul_f32 v[104:105], v[96:97], v[122:123]
	v_pk_mul_f32 v[106:107], v[98:99], v[122:123]
	v_exp_f32_e32 v104, v104
	v_exp_f32_e32 v105, v105
	v_exp_f32_e32 v106, v106
	v_exp_f32_e32 v107, v107
	v_pk_add_f32 v[104:105], v[104:105], v[124:125]
	v_pk_add_f32 v[106:107], v[106:107], v[124:125]
	v_rcp_f32_e32 v104, v104
	v_rcp_f32_e32 v105, v105
	v_rcp_f32_e32 v106, v106
	v_rcp_f32_e32 v107, v107
	v_pk_mul_f32 v[104:105], v[96:97], v[104:105]
	v_pk_mul_f32 v[106:107], v[98:99], v[106:107]
	v_pk_mul_f32 v[108:109], v[100:101], v[104:105]
	v_pk_mul_f32 v[110:111], v[102:103], v[106:107]
	v_cvt_pk_bf16_f32 v112, v108, v109
	v_cvt_pk_bf16_f32 v113, v110, v111
	global_store_dwordx2 v[68:69], v[112:113], off
	v_lshl_add_u64 v[68:69], v[68:69], 0, s[58:59]
	v_pk_fma_f32 v[96:97], v[10:11], v[72:73], v[2:3]
	v_pk_fma_f32 v[98:99], v[12:13], v[74:75], v[4:5]
	v_pk_fma_f32 v[100:101], v[14:15], v[76:77], v[6:7]
	v_pk_fma_f32 v[102:103], v[16:17], v[78:79], v[8:9]
	v_pk_fma_f32 v[96:97], v[18:19], v[80:81], v[96:97]
	v_pk_fma_f32 v[98:99], v[20:21], v[82:83], v[98:99]
	v_pk_fma_f32 v[100:101], v[22:23], v[84:85], v[100:101]
	v_pk_fma_f32 v[102:103], v[24:25], v[86:87], v[102:103]
	s_waitcnt lgkmcnt(0)
	v_lshlrev_b32_e32 v88, 16, v118
	v_and_b32_e32 v89, 0xffff0000, v118
	v_lshlrev_b32_e32 v90, 16, v119
	v_and_b32_e32 v91, 0xffff0000, v119
	v_lshlrev_b32_e32 v92, 16, v120
	v_and_b32_e32 v93, 0xffff0000, v120
	v_lshlrev_b32_e32 v94, 16, v121
	v_and_b32_e32 v95, 0xffff0000, v121
	v_pk_fma_f32 v[96:97], v[26:27], v[88:89], v[96:97]
	v_pk_fma_f32 v[98:99], v[28:29], v[90:91], v[98:99]
	v_pk_fma_f32 v[100:101], v[30:31], v[92:93], v[100:101]
	v_pk_fma_f32 v[102:103], v[32:33], v[94:95], v[102:103]
	v_pk_mul_f32 v[104:105], v[96:97], v[122:123]
	v_pk_mul_f32 v[106:107], v[98:99], v[122:123]
	v_exp_f32_e32 v104, v104
	v_exp_f32_e32 v105, v105
	v_exp_f32_e32 v106, v106
	v_exp_f32_e32 v107, v107
	v_pk_add_f32 v[104:105], v[104:105], v[124:125]
	v_pk_add_f32 v[106:107], v[106:107], v[124:125]
	v_rcp_f32_e32 v104, v104
	v_rcp_f32_e32 v105, v105
	v_rcp_f32_e32 v106, v106
	v_rcp_f32_e32 v107, v107
	v_pk_mul_f32 v[104:105], v[96:97], v[104:105]
	v_pk_mul_f32 v[106:107], v[98:99], v[106:107]
	v_pk_mul_f32 v[108:109], v[100:101], v[104:105]
	v_pk_mul_f32 v[110:111], v[102:103], v[106:107]
	v_cvt_pk_bf16_f32 v112, v108, v109
	v_cvt_pk_bf16_f32 v113, v110, v111
	global_store_dwordx2 v[68:69], v[112:113], off
	s_or_b64 exec, exec, s[38:39]
	s_add_i32 s84, s84, s33
	s_cmpk_lt_i32 s84, 0x596
	s_barrier
	s_cbranch_scc1 .LBB0_2352
